# passC staging: 15 tile loads in flight before the LDS writes (was a 15-step load/wait/ds_write ladder)
# baseline (speedup 1.0000x reference)
; #define LAS __attribute__((address_space(3)))
; __device__ __forceinline__ void gla_passC(LAS unsigned char* lds, int uidx, const bf16_t* PR, const bf16_t* SUB, const bf16_t* QT, const bf16_t* AM, const float* gn  ,
;                                           bf16_t* Y, int tid, int wid, int lane) {
;     ...
;     u32x4 ogr[4];
;     { const bf16_t* gp0 = PR + (size_t)(tok0 + (tid >> 3)) * PRW + 3072 + h * DV + (tid & 7) * 32;
; #pragma unroll
;       for (int j = 0; j < 4; ++j) ogr[j] = *(const u32x4*)(gp0 + 8 * j); }
;     { const bf16_t* sp = SUB + ((size_t)bh * NCH + c) * (DK * DV);
; #pragma unroll
;       for (int i = 0; i < 8; ++i) { const int id = tid + 512 * i, k = id >> 5, cc = id & 31; *(LAS u32x4*)(Sn + k * 272 + cc * 8) = *(const u32x4*)(sp + k * DV + cc * 8); } }
; #pragma unroll
;     for (int i = 0; i < 2; ++i) { const int id = tid + 512 * i, row = id >> 4, cc = id & 15; *(LAS u32x4*)(Qs + row * 136 + cc * 8) = *(const u32x4*)(QT + (size_t)(tok0 + row) * QKD + h * DK + cc * 8); }
;     { const int row = tid >> 3, cc = tid & 7; *(LAS u32x4*)(As + row * 72 + cc * 8) = *(const u32x4*)(AM + (size_t)uidx * 4096 + row * 64 + cc * 8); }
;     stage_v(Vn, PR, tok0, h, tid);
;     __syncthreads();
.LBB0_487:
	s_ashr_i32 s10, s6, 7
	s_bfe_u32 s25, s6, 0x50002
	s_lshl_b32 s22, s10, 11
	s_lshl_b32 s23, s25, 6
	s_and_b32 s7, s6, 3
	s_or_b32 s24, s23, s22
	s_lshl_b32 s10, s10, 2
	s_or_b32 s26, s10, s7
	v_add_u32_e32 v74, s24, v78
	v_ashrrev_i32_e32 v75, 31, v74
	s_ashr_i32 s27, s26, 31
	v_lshlrev_b64 v[0:1], 13, v[74:75]
	s_lshl_b32 s10, s7, 8
	s_lshl_b32 s22, s7, 9
	s_lshl_b64 s[26:27], s[26:27], 21
	v_lshl_add_u64 v[0:1], s[4:5], 0, v[0:1]
	s_mov_b32 s23, s11
	s_add_u32 s26, s8, s26
	v_lshl_add_u64 v[0:1], v[0:1], 0, s[22:23]
	s_addc_u32 s27, s9, s27
	s_lshl_b32 s25, s25, 16
	v_lshl_add_u64 v[0:1], v[0:1], 0, v[168:169]
	s_mov_b64 s[28:29], 0x1800
	s_add_u32 s26, s26, s25
	v_lshl_add_u64 v[8:9], v[0:1], 0, s[28:29]
	v_add_co_u32_e32 v0, vcc, s15, v0
	s_addc_u32 s27, s27, 0
	v_mov_b32_e32 v71, v169
	v_addc_co_u32_e32 v1, vcc, 0, v1, vcc
	v_lshl_add_u64 v[12:13], s[26:27], 0, v[70:71]
	global_load_dwordx4 v[36:39], v[0:1], off offset:2048
	s_nop 0
	global_load_dwordx4 v[0:3], v[8:9], off offset:48
	global_load_dwordx4 v[4:7], v[8:9], off offset:32
	global_load_dwordx4 v[20:23], v[8:9], off offset:16
	v_lshl_add_u64 v[8:9], v[48:49], 1, v[12:13]
	global_load_dwordx4 v[128:131], v[8:9], off
	v_lshlrev_b64 v[74:75], 12, v[74:75]
	v_lshl_add_u64 v[74:75], s[2:3], 0, v[74:75]
	v_lshl_add_u64 v[74:75], v[74:75], 0, s[22:23]
	s_add_i32 s6, s6, s82
	v_lshl_add_u64 v[8:9], v[50:51], 1, v[12:13]
	global_load_dwordx4 v[132:135], v[8:9], off
	v_lshl_add_u64 v[8:9], v[52:53], 1, v[12:13]
	global_load_dwordx4 v[136:139], v[8:9], off
	v_lshl_add_u64 v[8:9], v[54:55], 1, v[12:13]
	global_load_dwordx4 v[140:143], v[8:9], off
	v_lshl_add_u64 v[8:9], v[56:57], 1, v[12:13]
	global_load_dwordx4 v[144:147], v[8:9], off
	v_lshl_add_u64 v[8:9], v[58:59], 1, v[12:13]
	global_load_dwordx4 v[148:151], v[8:9], off
	v_lshl_add_u64 v[8:9], v[60:61], 1, v[12:13]
	global_load_dwordx4 v[152:155], v[8:9], off
	v_lshl_add_u64 v[8:9], v[62:63], 1, v[12:13]
	global_load_dwordx4 v[156:159], v[8:9], off
	v_lshl_add_u64 v[12:13], v[64:65], 0, s[10:11]
	s_lshl_b32 s10, s7, 10
	s_mov_b32 s7, 0x18c84000
	s_cmpk_gt_i32 s6, 0x1ff
	v_add_u32_e32 v8, s24, v83
	v_ashrrev_i32_e32 v9, 31, v8
	v_lshlrev_b64 v[8:9], 10, v[8:9]
	v_lshl_add_u64 v[8:9], v[12:13], 0, v[8:9]
	global_load_dwordx4 v[160:163], v[8:9], off
	v_add_u32_e32 v8, s24, v84
	v_ashrrev_i32_e32 v9, 31, v8
	v_lshlrev_b64 v[8:9], 10, v[8:9]
	v_lshl_add_u64 v[8:9], v[12:13], 0, v[8:9]
	global_load_dwordx4 v[164:167], v[8:9], off
	global_load_dwordx4 v[178:181], v[68:69], off
	v_lshl_add_u64 v[68:69], v[68:69], 0, s[34:35]
	v_add_u32_e32 v8, s24, v79
	v_ashrrev_i32_e32 v9, 31, v8
	v_lshlrev_b64 v[8:9], 13, v[8:9]
	v_lshl_add_u64 v[8:9], s[4:5], 0, v[8:9]
	v_lshl_add_u64 v[8:9], v[8:9], 0, s[22:23]
	v_lshl_add_u64 v[8:9], v[8:9], 0, v[70:71]
	v_add_co_u32_e32 v8, vcc, s15, v8
	s_nop 1
	v_addc_co_u32_e32 v9, vcc, 0, v9, vcc
	global_load_dwordx4 v[182:185], v[8:9], off
	v_add_u32_e32 v8, s24, v80
	v_ashrrev_i32_e32 v9, 31, v8
	v_lshlrev_b64 v[8:9], 13, v[8:9]
	v_lshl_add_u64 v[8:9], s[4:5], 0, v[8:9]
	v_lshl_add_u64 v[8:9], v[8:9], 0, s[22:23]
	v_lshl_add_u64 v[8:9], v[8:9], 0, v[70:71]
	v_add_co_u32_e32 v8, vcc, s15, v8
	s_nop 1
	v_addc_co_u32_e32 v9, vcc, 0, v9, vcc
	global_load_dwordx4 v[186:189], v[8:9], off
	v_add_u32_e32 v8, s24, v81
	v_ashrrev_i32_e32 v9, 31, v8
	v_lshlrev_b64 v[8:9], 13, v[8:9]
	v_lshl_add_u64 v[8:9], s[4:5], 0, v[8:9]
	v_lshl_add_u64 v[8:9], v[8:9], 0, s[22:23]
	v_lshl_add_u64 v[8:9], v[8:9], 0, v[70:71]
	v_add_co_u32_e32 v8, vcc, s15, v8
	s_nop 1
	v_addc_co_u32_e32 v9, vcc, 0, v9, vcc
	global_load_dwordx4 v[190:193], v[8:9], off
	v_add_u32_e32 v8, s24, v82
	v_ashrrev_i32_e32 v9, 31, v8
	v_lshlrev_b64 v[8:9], 13, v[8:9]
	v_lshl_add_u64 v[8:9], s[4:5], 0, v[8:9]
	v_lshl_add_u64 v[8:9], v[8:9], 0, s[22:23]
	v_lshl_add_u64 v[8:9], v[8:9], 0, v[70:71]
	v_add_co_u32_e32 v8, vcc, s15, v8
	s_mov_b64 s[22:23], 0x18c84800
	s_nop 0
	v_addc_co_u32_e32 v9, vcc, 0, v9, vcc
	global_load_dwordx4 v[194:197], v[8:9], off
	s_waitcnt vmcnt(14)
	ds_write_b128 v92, v[128:131] offset:61440
	s_waitcnt vmcnt(13)
	ds_write_b128 v93, v[132:135] offset:61440
	s_waitcnt vmcnt(12)
	ds_write_b128 v94, v[136:139] offset:61440
	s_waitcnt vmcnt(11)
	ds_write_b128 v95, v[140:143] offset:61440
	s_waitcnt vmcnt(10)
	ds_write_b128 v96, v[144:147] offset:61440
	s_waitcnt vmcnt(9)
	ds_write_b128 v97, v[148:151] offset:61440
	s_waitcnt vmcnt(8)
	ds_write_b128 v98, v[152:155] offset:61440
	s_waitcnt vmcnt(7)
	ds_write_b128 v99, v[156:159] offset:61440
	s_waitcnt vmcnt(6)
	ds_write_b128 v100, v[160:163]
	s_waitcnt vmcnt(5)
	ds_write_b128 v101, v[164:167]
	s_waitcnt vmcnt(4)
	ds_write_b128 v85, v[178:181] offset:17408
	s_waitcnt vmcnt(3)
	ds_write_b128 v92, v[182:185] offset:26624
	s_waitcnt vmcnt(2)
	ds_write_b128 v93, v[186:189] offset:26624
	s_waitcnt vmcnt(1)
	ds_write_b128 v94, v[190:193] offset:26624
	s_waitcnt vmcnt(0)
	ds_write_b128 v95, v[194:197] offset:26624
	s_waitcnt lgkmcnt(0)
	s_barrier
; #define LAS __attribute__((address_space(3)))
; #define MFMA16(x, y, c) __builtin_amdgcn_mfma_f32_16x16x32_bf16((x), (y), (c), 0, 0, 0)
; __device__ __forceinline__ void gla_passC(LAS unsigned char* lds, int uidx, const bf16_t* PR, const bf16_t* SUB, const bf16_t* QT, const bf16_t* AM, const float* gn  ,
;                                           bf16_t* Y, int tid, int wid, int lane) {
;     ...
;     f32x4 acc[2][4];
; #pragma unroll
;     for (int a = 0; a < 2; ++a)
; #pragma unroll
;         for (int it = 0; it < 4; ++it) acc[a][it] = (f32x4){0.f, 0.f, 0.f, 0.f};
; #pragma unroll
;     for (int ks = 0; ks < 4; ++ks) { bf16x8 x[2];
; #pragma unroll
;         for (int a = 0; a < 2; ++a) x[a] = tr_frag<272>(Sn, 2 * wid + a, ks, lane);
; #pragma unroll
;         for (int it = 0; it < 4; ++it) { const bf16x8 y = *(const LAS bf16x8*)(Qs + (16 * it + r) * 136 + 32 * ks + 8 * q);
; #pragma unroll
;             for (int a = 0; a < 2; ++a) acc[a][it] = MFMA16(x[a], y, acc[a][it]); } }
; #pragma unroll
;     for (int ks = 0; ks < 2; ++ks) { bf16x8 x[2];
; #pragma unroll
;         for (int a = 0; a < 2; ++a) x[a] = tr_frag<272>(Vn, 2 * wid + a, ks, lane);
; #pragma unroll
;         for (int it = 0; it < 4; ++it) { const bf16x8 y = *(const LAS bf16x8*)(As + (16 * it + r) * 72 + 32 * ks + 8 * q);
; #pragma unroll
;             for (int a = 0; a < 2; ++a) acc[a][it] = MFMA16(x[a], y, acc[a][it]); } }
	ds_read_u16 v8, v86 offset:61440
	ds_read_u16 v12, v86 offset:61984
	ds_read_u16 v9, v86 offset:62528
	ds_read_u16 v13, v86 offset:63072
	ds_read_u16 v10, v86 offset:63616
	ds_read_u16 v14, v86 offset:64160
	ds_read_u16 v11, v86 offset:64704
	ds_read_u16 v15, v86 offset:65248
	ds_read_u16 v24, v86 offset:61472
	ds_read_u16 v28, v86 offset:62016
	ds_read_u16 v25, v86 offset:62560
	ds_read_u16 v29, v86 offset:63104
	ds_read_u16 v26, v86 offset:63648
	ds_read_u16 v30, v86 offset:64192
	ds_read_u16 v27, v86 offset:64736
	ds_read_u16 v31, v86 offset:65280
	s_waitcnt lgkmcnt(8)
	v_perm_b32 v11, v15, v11, s13
	v_perm_b32 v10, v14, v10, s13
	v_perm_b32 v9, v13, v9, s13
	v_perm_b32 v8, v12, v8, s13
	ds_read_b128 v[12:15], v102
	s_waitcnt lgkmcnt(1)
	v_perm_b32 v27, v31, v27, s13
	v_perm_b32 v26, v30, v26, s13
	v_perm_b32 v25, v29, v25, s13
	v_perm_b32 v24, v28, v24, s13
	ds_read_b128 v[28:31], v102 offset:4352
	ds_read_b128 v[40:43], v102 offset:8704
	ds_read_b128 v[110:113], v102 offset:13056
	s_waitcnt lgkmcnt(3)
	v_mfma_f32_16x16x32_bf16 v[16:19], v[8:11], v[12:15], 0
	v_mfma_f32_16x16x32_bf16 v[12:15], v[24:27], v[12:15], 0
	s_waitcnt lgkmcnt(2)
	v_mfma_f32_16x16x32_bf16 v[32:35], v[8:11], v[28:31], 0
	v_mfma_f32_16x16x32_bf16 v[28:31], v[24:27], v[28:31], 0
	s_waitcnt lgkmcnt(1)
	v_mfma_f32_16x16x32_bf16 v[44:47], v[8:11], v[40:43], 0
	v_mfma_f32_16x16x32_bf16 v[40:43], v[24:27], v[40:43], 0
	s_waitcnt lgkmcnt(0)
	v_mfma_f32_16x16x32_bf16 v[8:11], v[8:11], v[110:113], 0
	v_mfma_f32_16x16x32_bf16 v[24:27], v[24:27], v[110:113], 0
	ds_read_u16 v71, v103 offset:61984
	ds_read_u16 v72, v103 offset:62528
	ds_read_u16 v73, v103 offset:63072
	ds_read_u16 v76, v103 offset:63616
	ds_read_u16 v77, v103 offset:64160
	ds_read_u16 v109, v103 offset:64704
	ds_read_u16 v110, v103 offset:65248
	ds_read_u16 v114, v103 offset:61440
	ds_read_u16 v118, v103 offset:61472
	ds_read_u16 v122, v103 offset:62016
	ds_read_u16 v119, v103 offset:62560
	ds_read_u16 v123, v103 offset:63104
	ds_read_u16 v120, v103 offset:63648
	ds_read_u16 v124, v103 offset:64192
	ds_read_u16 v121, v103 offset:64736
	ds_read_u16 v125, v103 offset:65280
	s_waitcnt lgkmcnt(9)
	v_perm_b32 v113, v110, v109, s13
	v_perm_b32 v112, v77, v76, s13
	v_perm_b32 v111, v73, v72, s13
	s_waitcnt lgkmcnt(8)
	v_perm_b32 v110, v71, v114, s13
	ds_read_b128 v[114:117], v102 offset:64
	s_waitcnt lgkmcnt(1)
	v_perm_b32 v121, v125, v121, s13
	v_perm_b32 v120, v124, v120, s13
	v_perm_b32 v119, v123, v119, s13
	v_perm_b32 v118, v122, v118, s13
	s_waitcnt lgkmcnt(0)
	v_mfma_f32_16x16x32_bf16 v[16:19], v[110:113], v[114:117], v[16:19]
	v_mfma_f32_16x16x32_bf16 v[12:15], v[118:121], v[114:117], v[12:15]
	ds_read_b128 v[114:117], v102 offset:4416
	s_waitcnt lgkmcnt(0)
	v_mfma_f32_16x16x32_bf16 v[32:35], v[110:113], v[114:117], v[32:35]
	v_mfma_f32_16x16x32_bf16 v[28:31], v[118:121], v[114:117], v[28:31]
	ds_read_b128 v[114:117], v102 offset:8768
	s_waitcnt lgkmcnt(0)
	v_mfma_f32_16x16x32_bf16 v[44:47], v[110:113], v[114:117], v[44:47]
	v_mfma_f32_16x16x32_bf16 v[40:43], v[118:121], v[114:117], v[40:43]
	ds_read_b128 v[114:117], v102 offset:13120
	s_waitcnt lgkmcnt(0)
	v_mfma_f32_16x16x32_bf16 v[8:11], v[110:113], v[114:117], v[8:11]
	v_mfma_f32_16x16x32_bf16 v[24:27], v[118:121], v[114:117], v[24:27]
	ds_read_u16 v71, v87 offset:35360
	ds_read_u16 v72, v87 offset:35904
	ds_read_u16 v73, v87 offset:36448
	ds_read_u16 v76, v87 offset:36992
	ds_read_u16 v77, v87 offset:37536
	ds_read_u16 v109, v87 offset:38080
	ds_read_u16 v110, v87 offset:38624
	ds_read_u16 v114, v87 offset:34816
	ds_read_u16 v118, v87 offset:34848
	ds_read_u16 v122, v87 offset:35392
	ds_read_u16 v119, v87 offset:35936
	ds_read_u16 v123, v87 offset:36480
	ds_read_u16 v120, v87 offset:37024
	ds_read_u16 v124, v87 offset:37568
	ds_read_u16 v121, v87 offset:38112
	ds_read_u16 v125, v87 offset:38656
	s_waitcnt lgkmcnt(9)
	v_perm_b32 v113, v110, v109, s13
	v_perm_b32 v112, v77, v76, s13
	v_perm_b32 v111, v73, v72, s13
	s_waitcnt lgkmcnt(8)
	v_perm_b32 v110, v71, v114, s13
	ds_read_b128 v[114:117], v102 offset:128
	s_waitcnt lgkmcnt(1)
	v_perm_b32 v121, v125, v121, s13
	v_perm_b32 v120, v124, v120, s13
	v_perm_b32 v119, v123, v119, s13
	v_perm_b32 v118, v122, v118, s13
	s_waitcnt lgkmcnt(0)
	v_mfma_f32_16x16x32_bf16 v[16:19], v[110:113], v[114:117], v[16:19]
	v_mfma_f32_16x16x32_bf16 v[12:15], v[118:121], v[114:117], v[12:15]
	ds_read_b128 v[114:117], v102 offset:4480
	s_waitcnt lgkmcnt(0)
	v_mfma_f32_16x16x32_bf16 v[32:35], v[110:113], v[114:117], v[32:35]
	v_mfma_f32_16x16x32_bf16 v[28:31], v[118:121], v[114:117], v[28:31]
	ds_read_b128 v[114:117], v102 offset:8832
	s_waitcnt lgkmcnt(0)
	v_mfma_f32_16x16x32_bf16 v[44:47], v[110:113], v[114:117], v[44:47]
	v_mfma_f32_16x16x32_bf16 v[40:43], v[118:121], v[114:117], v[40:43]
	ds_read_b128 v[114:117], v102 offset:13184
	s_waitcnt lgkmcnt(0)
	v_mfma_f32_16x16x32_bf16 v[8:11], v[110:113], v[114:117], v[8:11]
	v_mfma_f32_16x16x32_bf16 v[24:27], v[118:121], v[114:117], v[24:27]
	ds_read_u16 v71, v87 offset:52224
	ds_read_u16 v72, v87 offset:52768
	ds_read_u16 v73, v87 offset:53312
	ds_read_u16 v76, v87 offset:53856
	ds_read_u16 v77, v87 offset:54400
	ds_read_u16 v109, v87 offset:54944
	ds_read_u16 v110, v87 offset:55488
	ds_read_u16 v111, v87 offset:56032
	ds_read_u16 v118, v87 offset:52256
	ds_read_u16 v122, v87 offset:52800
	ds_read_u16 v119, v87 offset:53344
	ds_read_u16 v123, v87 offset:53888
	ds_read_u16 v120, v87 offset:54432
	ds_read_u16 v124, v87 offset:54976
	ds_read_u16 v121, v87 offset:55520
	ds_read_u16 v125, v87 offset:56064
	s_waitcnt lgkmcnt(8)
; #define LAS __attribute__((address_space(3)))
; #define MFMA16(x, y, c) __builtin_amdgcn_mfma_f32_16x16x32_bf16((x), (y), (c), 0, 0, 0)
; __device__ __forceinline__ void gla_passC(LAS unsigned char* lds, int uidx, const bf16_t* PR, const bf16_t* SUB, const bf16_t* QT, const bf16_t* AM, const float* gn  ,
;                                           bf16_t* Y, int tid, int wid, int lane) {
;     ...
;     for (int ks = 0; ks < 2; ++ks) { bf16x8 x[2];
; #pragma unroll
;         for (int a = 0; a < 2; ++a) x[a] = tr_frag<272>(Vn, 2 * wid + a, ks, lane);
; #pragma unroll
;         for (int it = 0; it < 4; ++it) { const bf16x8 y = *(const LAS bf16x8*)(As + (16 * it + r) * 72 + 32 * ks + 8 * q);
; #pragma unroll
;             for (int a = 0; a < 2; ++a) acc[a][it] = MFMA16(x[a], y, acc[a][it]); } }
;     __syncthreads();
; #pragma unroll
;     for (int a = 0; a < 2; ++a)
; #pragma unroll
;         for (int it = 0; it < 4; ++it) *(LAS f32x4*)(Of + (16 * it + r) * 260 + 32 * wid + 16 * a + 4 * q) = acc[a][it];
;     __syncthreads();
	v_perm_b32 v113, v111, v110, s13
	v_perm_b32 v112, v109, v77, s13
	v_perm_b32 v111, v76, v73, s13
	v_perm_b32 v110, v72, v71, s13
	ds_read_b128 v[114:117], v102 offset:192
	s_waitcnt lgkmcnt(1)
	v_perm_b32 v121, v125, v121, s13
	v_perm_b32 v120, v124, v120, s13
	v_perm_b32 v119, v123, v119, s13
	v_perm_b32 v118, v122, v118, s13
	s_waitcnt lgkmcnt(0)
	v_mfma_f32_16x16x32_bf16 v[16:19], v[110:113], v[114:117], v[16:19]
	v_mfma_f32_16x16x32_bf16 v[12:15], v[118:121], v[114:117], v[12:15]
	ds_read_b128 v[114:117], v102 offset:4544
	s_waitcnt lgkmcnt(0)
	v_mfma_f32_16x16x32_bf16 v[32:35], v[110:113], v[114:117], v[32:35]
	v_mfma_f32_16x16x32_bf16 v[28:31], v[118:121], v[114:117], v[28:31]
	ds_read_b128 v[114:117], v102 offset:8896
	s_waitcnt lgkmcnt(0)
	v_mfma_f32_16x16x32_bf16 v[44:47], v[110:113], v[114:117], v[44:47]
	v_mfma_f32_16x16x32_bf16 v[40:43], v[118:121], v[114:117], v[40:43]
	ds_read_b128 v[114:117], v102 offset:13248
	s_waitcnt lgkmcnt(0)
	v_mfma_f32_16x16x32_bf16 v[8:11], v[110:113], v[114:117], v[8:11]
	v_mfma_f32_16x16x32_bf16 v[24:27], v[118:121], v[114:117], v[24:27]
	ds_read_u16 v71, v86 offset:27168
	ds_read_u16 v72, v86 offset:27712
	ds_read_u16 v73, v86 offset:28256
	ds_read_u16 v76, v86 offset:28800
	ds_read_u16 v77, v86 offset:29344
	ds_read_u16 v109, v86 offset:29888
	ds_read_u16 v110, v86 offset:30432
	ds_read_u16 v114, v86 offset:26624
	ds_read_u16 v118, v86 offset:26656
	ds_read_u16 v122, v86 offset:27200
	ds_read_u16 v119, v86 offset:27744
	ds_read_u16 v123, v86 offset:28288
	ds_read_u16 v120, v86 offset:28832
	ds_read_u16 v124, v86 offset:29376
	ds_read_u16 v121, v86 offset:29920
	ds_read_u16 v125, v86 offset:30464
	s_waitcnt lgkmcnt(9)
	v_perm_b32 v113, v110, v109, s13
	v_perm_b32 v112, v77, v76, s13
	v_perm_b32 v111, v73, v72, s13
	s_waitcnt lgkmcnt(8)
	v_perm_b32 v110, v71, v114, s13
	ds_read_b128 v[114:117], v104 offset:17408
	s_waitcnt lgkmcnt(1)
	v_perm_b32 v121, v125, v121, s13
	v_perm_b32 v120, v124, v120, s13
	v_perm_b32 v119, v123, v119, s13
	v_perm_b32 v118, v122, v118, s13
	s_waitcnt lgkmcnt(0)
	v_mfma_f32_16x16x32_bf16 v[16:19], v[110:113], v[114:117], v[16:19]
	v_mfma_f32_16x16x32_bf16 v[12:15], v[118:121], v[114:117], v[12:15]
	ds_read_b128 v[114:117], v104 offset:19712
	s_waitcnt lgkmcnt(0)
	v_mfma_f32_16x16x32_bf16 v[32:35], v[110:113], v[114:117], v[32:35]
	v_mfma_f32_16x16x32_bf16 v[28:31], v[118:121], v[114:117], v[28:31]
	ds_read_b128 v[114:117], v104 offset:22016
	s_waitcnt lgkmcnt(0)
	v_mfma_f32_16x16x32_bf16 v[44:47], v[110:113], v[114:117], v[44:47]
	v_mfma_f32_16x16x32_bf16 v[40:43], v[118:121], v[114:117], v[40:43]
	ds_read_b128 v[114:117], v104 offset:24320
	s_waitcnt lgkmcnt(0)
	v_mfma_f32_16x16x32_bf16 v[8:11], v[110:113], v[114:117], v[8:11]
	v_mfma_f32_16x16x32_bf16 v[24:27], v[118:121], v[114:117], v[24:27]
	ds_read_u16 v71, v86 offset:44032
	ds_read_u16 v72, v86 offset:44576
	ds_read_u16 v73, v86 offset:45120
	ds_read_u16 v76, v86 offset:45664
	ds_read_u16 v77, v86 offset:46208
	ds_read_u16 v109, v86 offset:46752
	ds_read_u16 v110, v86 offset:47296
	ds_read_u16 v111, v86 offset:47840
	ds_read_u16 v118, v86 offset:44064
	ds_read_u16 v122, v86 offset:44608
	ds_read_u16 v119, v86 offset:45152
	ds_read_u16 v123, v86 offset:45696
	ds_read_u16 v120, v86 offset:46240
	ds_read_u16 v124, v86 offset:46784
	ds_read_u16 v121, v86 offset:47328
	ds_read_u16 v125, v86 offset:47872
	s_waitcnt lgkmcnt(8)
	v_perm_b32 v113, v111, v110, s13
	v_perm_b32 v112, v109, v77, s13
	v_perm_b32 v111, v76, v73, s13
	v_perm_b32 v110, v72, v71, s13
	ds_read_b128 v[114:117], v104 offset:17472
	s_waitcnt lgkmcnt(1)
	v_perm_b32 v121, v125, v121, s13
	v_perm_b32 v120, v124, v120, s13
	v_perm_b32 v119, v123, v119, s13
	v_perm_b32 v118, v122, v118, s13
	s_waitcnt lgkmcnt(0)
	v_mfma_f32_16x16x32_bf16 v[16:19], v[110:113], v[114:117], v[16:19]
	v_mfma_f32_16x16x32_bf16 v[12:15], v[118:121], v[114:117], v[12:15]
	ds_read_b128 v[114:117], v104 offset:19776
	s_waitcnt lgkmcnt(0)
	v_mfma_f32_16x16x32_bf16 v[32:35], v[110:113], v[114:117], v[32:35]
	v_mfma_f32_16x16x32_bf16 v[28:31], v[118:121], v[114:117], v[28:31]
	ds_read_b128 v[114:117], v104 offset:22080
	s_waitcnt lgkmcnt(0)
	v_mfma_f32_16x16x32_bf16 v[44:47], v[110:113], v[114:117], v[44:47]
	v_mfma_f32_16x16x32_bf16 v[40:43], v[118:121], v[114:117], v[40:43]
	ds_read_b128 v[114:117], v104 offset:24384
	s_waitcnt lgkmcnt(0)
	s_barrier
	v_mfma_f32_16x16x32_bf16 v[8:11], v[110:113], v[114:117], v[8:11]
	v_mfma_f32_16x16x32_bf16 v[24:27], v[118:121], v[114:117], v[24:27]
	ds_write_b128 v105, v[16:19] offset:61440
	ds_write_b128 v106, v[32:35] offset:61440
	ds_write_b128 v107, v[44:47] offset:61440
	s_nop 3
	ds_write_b128 v108, v[8:11] offset:61440
	ds_write_b128 v105, v[12:15] offset:61504
	ds_write_b128 v106, v[28:31] offset:61504
	ds_write_b128 v107, v[40:43] offset:61504
	ds_write_b128 v108, v[24:27] offset:61504
	s_waitcnt lgkmcnt(0)
	s_barrier
; __device__ __forceinline__ unsigned cvt_pk_bf16(float lo, float hi) { unsigned r; asm volatile("v_cvt_pk_bf16_f32 %0, %1, %2" : "=v"(r) : "v"(lo), "v"(hi)); return r; }
; #define LAS __attribute__((address_space(3)))
; __device__ __forceinline__ float bf_lo(unsigned w) { return __uint_as_float(w << 16); }
; __device__ __forceinline__ float bf_hi(unsigned w) { return __uint_as_float(w & 0xffff0000u); }
; __device__ __forceinline__ float silu_f(float x) { return x * __builtin_amdgcn_rcpf(1.f + __expf(-x)); }
; __device__ __forceinline__ void gla_passC(LAS unsigned char* lds, int uidx, const bf16_t* PR, const bf16_t* SUB, const bf16_t* QT, const bf16_t* AM, const float* gn  ,
;                                           bf16_t* Y, int tid, int wid, int lane) {
;     ...
;     { const int i = tid >> 3, seg = tid & 7; f32x4 o[8]; float ss = 0.f;
; #pragma unroll
;       for (int j = 0; j < 8; ++j) { o[j] = *(const LAS f32x4*)(Of + i * 260 + seg * 32 + 4 * j); ss += (o[j].x * o[j].x + o[j].y * o[j].y) + (o[j].z * o[j].z + o[j].w * o[j].w); }
;       ss += __shfl_xor(ss, 1); ss += __shfl_xor(ss, 2); ss += __shfl_xor(ss, 4);
;       const float rstd = rsqrtf(ss * (1.f / DV) + EPS);
;       const bf16_t* gp = PR + (size_t)(tok0 + i) * PRW + 3072 + h * DV + seg * 32; const float* gnp = gn + h * DV + seg * 32; bf16_t* yp = Y + (size_t)(tok0 + i) * DM + 1024 + h * DV + seg * 32;
; #pragma unroll
;       for (int j = 0; j < 4; ++j) { const u32x4 g = ogr[j]; const f32x4 n0 = *(const f32x4*)(gnp + 8 * j), n1 = *(const f32x4*)(gnp + 8 * j + 4); const f32x4 a0 = o[2 * j], a1 = o[2 * j + 1]; u32x4 w;
;           w.x = cvt_pk_bf16(a0.x * rstd * n0.x * silu_f(bf_lo(g.x)), a0.y * rstd * n0.y * silu_f(bf_hi(g.x)));
;           w.y = cvt_pk_bf16(a0.z * rstd * n0.z * silu_f(bf_lo(g.y)), a0.w * rstd * n0.w * silu_f(bf_hi(g.y)));
;           w.z = cvt_pk_bf16(a1.x * rstd * n1.x * silu_f(bf_lo(g.z)), a1.y * rstd * n1.y * silu_f(bf_hi(g.z)));
;           w.w = cvt_pk_bf16(a1.z * rstd * n1.z * silu_f(bf_lo(g.w)), a1.w * rstd * n1.w * silu_f(bf_hi(g.w)));
;           *(u32x4*)(yp + 8 * j) = w; } }
	ds_read_b128 v[44:47], v88 offset:61440
	ds_read_b128 v[40:43], v88 offset:61456
	ds_read_b128 v[32:35], v88 offset:61472
	ds_read_b128 v[28:31], v88 offset:61488
	ds_read_b128 v[24:27], v88 offset:61504
	ds_read_b128 v[16:19], v88 offset:61520
	s_waitcnt lgkmcnt(5)
	v_mov_b32_e32 v10, v45
	s_waitcnt lgkmcnt(4)
	v_mov_b32_e32 v11, v41
	v_mov_b32_e32 v8, v44
	v_mov_b32_e32 v9, v40
	v_pk_mul_f32 v[10:11], v[10:11], v[10:11]
	v_mov_b32_e32 v12, v47
	v_mov_b32_e32 v13, v43
	v_pk_fma_f32 v[8:9], v[8:9], v[8:9], v[10:11]
	v_mov_b32_e32 v10, v46
	v_mov_b32_e32 v11, v42
	v_pk_mul_f32 v[12:13], v[12:13], v[12:13]
	v_lshlrev_b32_e32 v118, 16, v36
	v_pk_fma_f32 v[10:11], v[10:11], v[10:11], v[12:13]
	s_waitcnt lgkmcnt(3)
	v_pk_mul_f32 v[12:13], v[32:33], v[32:33]
	v_pk_add_f32 v[8:9], v[8:9], v[10:11]
	v_pk_mul_f32 v[10:11], v[34:35], v[34:35]
	v_pk_add_f32 v[8:9], v[8:9], v[8:9] op_sel:[0,1] op_sel_hi:[1,0]
	v_pk_mov_b32 v[14:15], v[12:13], v[10:11] op_sel:[1,0]
	v_mov_b32_e32 v13, v11
	v_pk_add_f32 v[10:11], v[14:15], v[12:13]
	s_waitcnt lgkmcnt(1)
	v_mul_f32_e32 v12, v24, v24
	v_mul_f32_e32 v13, v25, v25
	v_pk_add_f32 v[10:11], v[10:11], v[10:11] op_sel:[0,1] op_sel_hi:[1,0]
	v_mov_b32_e32 v9, v12
	v_mov_b32_e32 v11, v13
	v_pk_add_f32 v[8:9], v[8:9], v[10:11]
	v_mul_f32_e32 v10, v29, v29
	v_mul_f32_e32 v12, v31, v31
	v_mul_f32_e32 v14, v26, v26
	v_mul_f32_e32 v15, v27, v27
	v_pk_fma_f32 v[10:11], v[28:29], v[28:29], v[10:11] op_sel_hi:[1,1,0]
	v_pk_fma_f32 v[12:13], v[30:31], v[30:31], v[12:13] op_sel_hi:[1,1,0]
	v_mov_b32_e32 v11, v14
	v_mov_b32_e32 v13, v15
	v_pk_add_f32 v[10:11], v[10:11], v[12:13]
	s_nop 0
	v_pk_add_f32 v[72:73], v[8:9], v[10:11]
	s_waitcnt lgkmcnt(0)
	v_pk_mul_f32 v[8:9], v[18:19], v[18:19]
	v_pk_mul_f32 v[10:11], v[16:17], v[16:17]
	v_pk_add_f32 v[72:73], v[72:73], v[72:73] op_sel:[0,1] op_sel_hi:[1,0]
	v_pk_mov_b32 v[12:13], v[10:11], v[8:9] op_sel:[1,0]
	v_mov_b32_e32 v11, v9
	v_pk_add_f32 v[76:77], v[12:13], v[10:11]
	ds_read_b128 v[12:15], v88 offset:61536
	ds_read_b128 v[8:11], v88 offset:61552
	v_pk_add_f32 v[76:77], v[76:77], v[76:77] op_sel:[0,1] op_sel_hi:[1,0]
	s_waitcnt lgkmcnt(0)
	v_mul_f32_e32 v71, v8, v8
	v_mul_f32_e32 v109, v9, v9
	v_mov_b32_e32 v73, v71
	v_mov_b32_e32 v77, v109
	v_pk_add_f32 v[72:73], v[72:73], v[76:77]
	v_mul_f32_e32 v76, v13, v13
	v_mul_f32_e32 v110, v10, v10
	v_pk_fma_f32 v[76:77], v[12:13], v[12:13], v[76:77] op_sel_hi:[1,1,0]
	v_mul_f32_e32 v112, v11, v11
	v_mov_b32_e32 v77, v110
	v_mul_f32_e32 v110, v15, v15
	v_pk_fma_f32 v[110:111], v[14:15], v[14:15], v[110:111] op_sel_hi:[1,1,0]
	s_nop 0
	v_mov_b32_e32 v111, v112
	v_pk_add_f32 v[76:77], v[76:77], v[110:111]
	s_nop 0
	v_pk_add_f32 v[72:73], v[72:73], v[76:77]
	v_lshl_add_u64 v[76:77], v[74:75], 0, v[168:169]
	v_add_f32_e32 v71, v72, v73
	ds_bpermute_b32 v72, v89, v71
	v_lshl_add_u64 v[74:75], v[76:77], 0, s[22:23]
	s_waitcnt lgkmcnt(0)
	v_add_f32_e32 v71, v71, v72
	ds_bpermute_b32 v72, v90, v71
	s_waitcnt lgkmcnt(0)
	v_add_f32_e32 v71, v71, v72
	ds_bpermute_b32 v72, v91, v71
	s_waitcnt lgkmcnt(0)
	v_add_f32_e32 v71, v71, v72
	v_fmamk_f32 v71, v71, 0x3b800000, v212
	v_cmp_gt_f32_e32 vcc, s14, v71
	v_mul_f32_e32 v72, 0x4b800000, v71
	s_nop 0
	v_cndmask_b32_e32 v71, v71, v72, vcc
	v_rsq_f32_e32 v71, v71
	s_nop 0
	v_mul_f32_e32 v72, 0x45800000, v71
	v_cndmask_b32_e32 v71, v71, v72, vcc
	v_lshl_add_u64 v[72:73], v[66:67], 0, s[10:11]
	global_load_dwordx4 v[110:113], v[72:73], off offset:16
	global_load_dwordx4 v[114:117], v[72:73], off
	v_mul_f32_e32 v119, v44, v71
	v_mul_f32_e32 v44, 0xbfb8aa3b, v118
	v_exp_f32_e32 v44, v44
	v_mul_f32_e32 v45, v45, v71
	v_mul_f32_e32 v41, v41, v71
	v_mul_f32_e32 v33, v33, v71
	v_add_f32_e32 v44, 1.0, v44
	v_rcp_f32_e32 v120, v44
	v_and_b32_e32 v44, 0xffff0000, v36
	v_mul_f32_e32 v36, 0xbfb8aa3b, v44
	v_exp_f32_e32 v36, v36
	v_mul_f32_e32 v29, v29, v71
	v_mul_f32_e32 v25, v25, v71
	v_mul_f32_e32 v17, v17, v71
	v_add_f32_e32 v36, 1.0, v36
	v_mul_f32_e32 v13, v13, v71
	v_mul_f32_e32 v9, v9, v71
	s_waitcnt vmcnt(0)
	v_mov_b32_e32 v121, v114
	v_rcp_f32_e32 v114, v36
	v_pk_mul_f32 v[118:119], v[120:121], v[118:119]
	v_pk_mul_f32 v[44:45], v[114:115], v[44:45]
	s_nop 0
	v_mul_f32_e32 v36, v44, v45
	v_lshlrev_b32_e32 v44, 16, v37
	v_mul_f32_e32 v45, v46, v71
	v_mul_f32_e32 v46, 0xbfb8aa3b, v44
	v_exp_f32_e32 v46, v46
	v_mov_b32_e32 v115, v116
	v_mul_f32_e32 v109, v118, v119
	v_cvt_pk_bf16_f32 v36, v109, v36
	v_add_f32_e32 v46, 1.0, v46
	v_rcp_f32_e32 v114, v46
	s_nop 0
	v_pk_mul_f32 v[44:45], v[114:115], v[44:45]
	s_nop 0
	v_mul_f32_e32 v46, v44, v45
	v_and_b32_e32 v44, 0xffff0000, v37
	v_mul_f32_e32 v37, 0xbfb8aa3b, v44
	v_exp_f32_e32 v37, v37
	v_mul_f32_e32 v45, v47, v71
	v_mov_b32_e32 v47, v110
	v_add_f32_e32 v37, 1.0, v37
	v_rcp_f32_e32 v116, v37
	s_nop 0
	v_pk_mul_f32 v[44:45], v[116:117], v[44:45]
	s_nop 0
	v_mul_f32_e32 v37, v44, v45
	v_lshlrev_b32_e32 v44, 16, v38
	v_mul_f32_e32 v45, v40, v71
	v_mul_f32_e32 v40, 0xbfb8aa3b, v44
	v_exp_f32_e32 v40, v40
	v_cvt_pk_bf16_f32 v37, v46, v37
	s_nop 0
	v_add_f32_e32 v40, 1.0, v40
	v_rcp_f32_e32 v46, v40
	v_and_b32_e32 v40, 0xffff0000, v38
	v_mul_f32_e32 v38, 0xbfb8aa3b, v40
	v_exp_f32_e32 v38, v38
	v_pk_mul_f32 v[44:45], v[46:47], v[44:45]
	v_add_f32_e32 v38, 1.0, v38
	v_rcp_f32_e32 v110, v38
	v_mul_f32_e32 v44, v44, v45
	v_mov_b32_e32 v45, v112
	v_pk_mul_f32 v[40:41], v[110:111], v[40:41]
	s_nop 0
	v_mul_f32_e32 v38, v40, v41
	v_lshlrev_b32_e32 v40, 16, v39
	v_mul_f32_e32 v41, v42, v71
	v_mul_f32_e32 v42, 0xbfb8aa3b, v40
	v_exp_f32_e32 v42, v42
	v_cvt_pk_bf16_f32 v38, v44, v38
	s_nop 0
	v_add_f32_e32 v42, 1.0, v42
	v_rcp_f32_e32 v44, v42
	s_nop 0
	v_pk_mul_f32 v[40:41], v[44:45], v[40:41]
	s_nop 0
	v_mul_f32_e32 v42, v40, v41
	v_and_b32_e32 v40, 0xffff0000, v39
	v_mul_f32_e32 v39, 0xbfb8aa3b, v40
	v_exp_f32_e32 v39, v39
	v_mul_f32_e32 v41, v43, v71
	v_lshlrev_b32_e32 v44, 16, v20
	v_mul_f32_e32 v45, v32, v71
	v_add_f32_e32 v39, 1.0, v39
	v_rcp_f32_e32 v112, v39
	v_mul_f32_e32 v32, 0xbfb8aa3b, v44
	v_exp_f32_e32 v32, v32
	v_pk_mul_f32 v[40:41], v[112:113], v[40:41]
	s_nop 0
	v_mul_f32_e32 v39, v40, v41
	v_add_co_u32_e32 v40, vcc, s7, v76
	v_cvt_pk_bf16_f32 v39, v42, v39
	v_add_f32_e32 v32, 1.0, v32
	s_nop 0
	v_addc_co_u32_e32 v41, vcc, 0, v77, vcc
	global_store_dwordx4 v[40:41], v[36:39], off offset:2048
	global_load_dwordx4 v[36:39], v[72:73], off offset:48
	s_nop 0
	global_load_dwordx4 v[40:43], v[72:73], off offset:32
	v_rcp_f32_e32 v46, v32
	v_and_b32_e32 v32, 0xffff0000, v20
	v_mul_f32_e32 v20, 0xbfb8aa3b, v32
	v_exp_f32_e32 v20, v20
	s_waitcnt vmcnt(0)
; __device__ __forceinline__ unsigned cvt_pk_bf16(float lo, float hi) { unsigned r; asm volatile("v_cvt_pk_bf16_f32 %0, %1, %2" : "=v"(r) : "v"(lo), "v"(hi)); return r; }
; __device__ __forceinline__ float bf_lo(unsigned w) { return __uint_as_float(w << 16); }
; __device__ __forceinline__ float bf_hi(unsigned w) { return __uint_as_float(w & 0xffff0000u); }
; __device__ __forceinline__ float silu_f(float x) { return x * __builtin_amdgcn_rcpf(1.f + __expf(-x)); }
; __device__ __forceinline__ void gla_passC(LAS unsigned char* lds, int uidx, const bf16_t* PR, const bf16_t* SUB, const bf16_t* QT, const bf16_t* AM, const float* gn  ,
;                                           bf16_t* Y, int tid, int wid, int lane) {
;     ...
;       for (int j = 0; j < 4; ++j) { const u32x4 g = ogr[j]; const f32x4 n0 = *(const f32x4*)(gnp + 8 * j), n1 = *(const f32x4*)(gnp + 8 * j + 4); const f32x4 a0 = o[2 * j], a1 = o[2 * j + 1]; u32x4 w;
;           w.x = cvt_pk_bf16(a0.x * rstd * n0.x * silu_f(bf_lo(g.x)), a0.y * rstd * n0.y * silu_f(bf_hi(g.x)));
;           w.y = cvt_pk_bf16(a0.z * rstd * n0.z * silu_f(bf_lo(g.y)), a0.w * rstd * n0.w * silu_f(bf_hi(g.y)));
;           w.z = cvt_pk_bf16(a1.x * rstd * n1.x * silu_f(bf_lo(g.z)), a1.y * rstd * n1.y * silu_f(bf_hi(g.z)));
;           w.w = cvt_pk_bf16(a1.z * rstd * n1.z * silu_f(bf_lo(g.w)), a1.w * rstd * n1.w * silu_f(bf_hi(g.w)));
;           *(u32x4*)(yp + 8 * j) = w; } }
;     __syncthreads();
	v_mov_b32_e32 v47, v40
	v_add_f32_e32 v20, 1.0, v20
	v_rcp_f32_e32 v40, v20
	v_pk_mul_f32 v[44:45], v[46:47], v[44:45]
	v_pk_mul_f32 v[32:33], v[40:41], v[32:33]
	s_nop 0
	v_mul_f32_e32 v20, v32, v33
	v_lshlrev_b32_e32 v32, 16, v21
	v_mul_f32_e32 v33, v34, v71
	v_mul_f32_e32 v34, 0xbfb8aa3b, v32
	v_exp_f32_e32 v34, v34
	v_mov_b32_e32 v41, v42
	v_mul_f32_e32 v44, v44, v45
	v_cvt_pk_bf16_f32 v20, v44, v20
	v_add_f32_e32 v34, 1.0, v34
	v_rcp_f32_e32 v40, v34
	s_nop 0
	v_pk_mul_f32 v[32:33], v[40:41], v[32:33]
	s_nop 0
	v_mul_f32_e32 v34, v32, v33
	v_and_b32_e32 v32, 0xffff0000, v21
	v_mul_f32_e32 v21, 0xbfb8aa3b, v32
	v_exp_f32_e32 v21, v21
	v_mul_f32_e32 v33, v35, v71
	v_mov_b32_e32 v35, v36
	v_add_f32_e32 v21, 1.0, v21
	v_rcp_f32_e32 v42, v21
	s_nop 0
	v_pk_mul_f32 v[32:33], v[42:43], v[32:33]
	s_nop 0
	v_mul_f32_e32 v21, v32, v33
	v_lshlrev_b32_e32 v32, 16, v22
	v_mul_f32_e32 v33, v28, v71
	v_mul_f32_e32 v28, 0xbfb8aa3b, v32
	v_exp_f32_e32 v28, v28
	v_cvt_pk_bf16_f32 v21, v34, v21
	s_nop 0
	v_add_f32_e32 v28, 1.0, v28
	v_rcp_f32_e32 v34, v28
	v_and_b32_e32 v28, 0xffff0000, v22
	v_mul_f32_e32 v22, 0xbfb8aa3b, v28
	v_exp_f32_e32 v22, v22
	v_pk_mul_f32 v[32:33], v[34:35], v[32:33]
	v_lshlrev_b32_e32 v34, 16, v4
	v_mul_f32_e32 v32, v32, v33
	v_add_f32_e32 v22, 1.0, v22
	v_rcp_f32_e32 v36, v22
	v_mov_b32_e32 v33, v38
	v_pk_mul_f32 v[28:29], v[36:37], v[28:29]
	s_nop 0
	v_mul_f32_e32 v22, v28, v29
	v_lshlrev_b32_e32 v28, 16, v23
	v_mul_f32_e32 v29, v30, v71
	v_mul_f32_e32 v30, 0xbfb8aa3b, v28
	v_exp_f32_e32 v30, v30
	v_cvt_pk_bf16_f32 v22, v32, v22
	s_nop 0
	v_add_f32_e32 v30, 1.0, v30
	v_rcp_f32_e32 v32, v30
	s_nop 0
	v_pk_mul_f32 v[28:29], v[32:33], v[28:29]
	s_nop 0
	v_mul_f32_e32 v30, v28, v29
	v_and_b32_e32 v28, 0xffff0000, v23
	v_mul_f32_e32 v23, 0xbfb8aa3b, v28
	v_exp_f32_e32 v23, v23
	v_mul_f32_e32 v29, v31, v71
	v_mul_f32_e32 v33, v24, v71
	v_mul_f32_e32 v24, 0xbfb8aa3b, v34
	v_add_f32_e32 v23, 1.0, v23
	v_rcp_f32_e32 v38, v23
	v_exp_f32_e32 v24, v24
	v_pk_mul_f32 v[28:29], v[38:39], v[28:29]
	s_nop 0
	v_mul_f32_e32 v23, v28, v29
	v_cvt_pk_bf16_f32 v23, v30, v23
	global_store_dwordx4 v[74:75], v[20:23], off offset:16
	global_load_dwordx4 v[20:23], v[72:73], off offset:80
	s_nop 0
	global_load_dwordx4 v[28:31], v[72:73], off offset:64
	v_add_f32_e32 v24, 1.0, v24
	v_rcp_f32_e32 v32, v24
	s_waitcnt vmcnt(0)
	v_mov_b32_e32 v35, v28
	v_and_b32_e32 v28, 0xffff0000, v4
	v_mul_f32_e32 v4, 0xbfb8aa3b, v28
	v_exp_f32_e32 v4, v4
	v_pk_mul_f32 v[32:33], v[32:33], v[34:35]
	v_add_f32_e32 v4, 1.0, v4
	v_rcp_f32_e32 v24, v4
	v_mul_f32_e32 v32, v32, v33
	v_pk_mul_f32 v[24:25], v[24:25], v[28:29]
	v_lshlrev_b32_e32 v28, 16, v5
	v_mul_f32_e32 v4, v24, v25
	v_mul_f32_e32 v24, 0xbfb8aa3b, v28
	v_exp_f32_e32 v24, v24
	v_mov_b32_e32 v29, v30
	v_and_b32_e32 v30, 0xffff0000, v5
	v_mul_f32_e32 v5, 0xbfb8aa3b, v30
	v_add_f32_e32 v24, 1.0, v24
	v_rcp_f32_e32 v24, v24
	v_exp_f32_e32 v5, v5
	v_mul_f32_e32 v25, v26, v71
	v_cvt_pk_bf16_f32 v4, v32, v4
	v_pk_mul_f32 v[24:25], v[24:25], v[28:29]
	v_add_f32_e32 v5, 1.0, v5
	v_mul_f32_e32 v26, v24, v25
	v_rcp_f32_e32 v24, v5
	v_mul_f32_e32 v25, v27, v71
	v_mov_b32_e32 v27, v20
	v_and_b32_e32 v20, 0xffff0000, v6
	v_pk_mul_f32 v[24:25], v[24:25], v[30:31]
	s_nop 0
	v_mul_f32_e32 v5, v24, v25
	v_cvt_pk_bf16_f32 v5, v26, v5
	v_lshlrev_b32_e32 v26, 16, v6
	v_mul_f32_e32 v25, v16, v71
	v_mul_f32_e32 v16, 0xbfb8aa3b, v26
	v_mul_f32_e32 v6, 0xbfb8aa3b, v20
	v_exp_f32_e32 v16, v16
	v_exp_f32_e32 v6, v6
	v_add_f32_e32 v16, 1.0, v16
	v_add_f32_e32 v6, 1.0, v6
	v_rcp_f32_e32 v24, v16
	v_rcp_f32_e32 v16, v6
	v_pk_mul_f32 v[24:25], v[24:25], v[26:27]
	v_pk_mul_f32 v[16:17], v[16:17], v[20:21]
	v_lshlrev_b32_e32 v20, 16, v7
	v_mul_f32_e32 v6, v16, v17
	v_mul_f32_e32 v16, 0xbfb8aa3b, v20
	v_exp_f32_e32 v16, v16
	v_mov_b32_e32 v21, v22
	v_and_b32_e32 v22, 0xffff0000, v7
	v_mul_f32_e32 v7, 0xbfb8aa3b, v22
	v_add_f32_e32 v16, 1.0, v16
	v_rcp_f32_e32 v16, v16
	v_exp_f32_e32 v7, v7
	v_mul_f32_e32 v17, v18, v71
	v_mul_f32_e32 v24, v24, v25
	v_pk_mul_f32 v[16:17], v[16:17], v[20:21]
	v_add_f32_e32 v7, 1.0, v7
	v_mul_f32_e32 v18, v16, v17
	v_rcp_f32_e32 v16, v7
	v_mul_f32_e32 v17, v19, v71
	v_cvt_pk_bf16_f32 v6, v24, v6
	v_mul_f32_e32 v21, v12, v71
	v_pk_mul_f32 v[16:17], v[16:17], v[22:23]
	v_lshlrev_b32_e32 v22, 16, v0
	v_mul_f32_e32 v7, v16, v17
	v_cvt_pk_bf16_f32 v7, v18, v7
	global_store_dwordx4 v[74:75], v[4:7], off offset:32
	global_load_dwordx4 v[4:7], v[72:73], off offset:112
	s_nop 0
	global_load_dwordx4 v[16:19], v[72:73], off offset:96
	v_mul_f32_e32 v12, 0xbfb8aa3b, v22
	v_exp_f32_e32 v12, v12
	s_waitcnt vmcnt(0)
	v_mov_b32_e32 v23, v16
	v_and_b32_e32 v16, 0xffff0000, v0
	v_mul_f32_e32 v0, 0xbfb8aa3b, v16
	v_exp_f32_e32 v0, v0
	v_add_f32_e32 v12, 1.0, v12
	v_rcp_f32_e32 v20, v12
	v_add_f32_e32 v0, 1.0, v0
	v_rcp_f32_e32 v12, v0
	v_pk_mul_f32 v[20:21], v[20:21], v[22:23]
	v_pk_mul_f32 v[12:13], v[12:13], v[16:17]
	v_lshlrev_b32_e32 v16, 16, v1
	v_mul_f32_e32 v0, v12, v13
	v_mul_f32_e32 v12, 0xbfb8aa3b, v16
	v_exp_f32_e32 v12, v12
	v_mov_b32_e32 v17, v18
	v_and_b32_e32 v18, 0xffff0000, v1
	v_mul_f32_e32 v1, 0xbfb8aa3b, v18
	v_add_f32_e32 v12, 1.0, v12
	v_rcp_f32_e32 v12, v12
	v_exp_f32_e32 v1, v1
	v_mul_f32_e32 v13, v14, v71
	v_mul_f32_e32 v20, v20, v21
	v_pk_mul_f32 v[12:13], v[12:13], v[16:17]
	v_add_f32_e32 v1, 1.0, v1
	v_mul_f32_e32 v14, v12, v13
	v_rcp_f32_e32 v12, v1
	v_mul_f32_e32 v13, v15, v71
	v_cvt_pk_bf16_f32 v0, v20, v0
	v_mov_b32_e32 v15, v4
	v_pk_mul_f32 v[12:13], v[12:13], v[18:19]
	v_and_b32_e32 v4, 0xffff0000, v2
	v_mul_f32_e32 v1, v12, v13
	v_cvt_pk_bf16_f32 v1, v14, v1
	v_lshlrev_b32_e32 v14, 16, v2
	v_mul_f32_e32 v13, v8, v71
	v_mul_f32_e32 v8, 0xbfb8aa3b, v14
	v_mul_f32_e32 v2, 0xbfb8aa3b, v4
	v_exp_f32_e32 v8, v8
	v_exp_f32_e32 v2, v2
	v_add_f32_e32 v8, 1.0, v8
	v_add_f32_e32 v2, 1.0, v2
	v_rcp_f32_e32 v12, v8
	v_rcp_f32_e32 v8, v2
	v_pk_mul_f32 v[12:13], v[12:13], v[14:15]
	v_pk_mul_f32 v[4:5], v[8:9], v[4:5]
	v_lshlrev_b32_e32 v8, 16, v3
	v_mul_f32_e32 v2, v4, v5
	v_mul_f32_e32 v4, 0xbfb8aa3b, v8
	v_exp_f32_e32 v4, v4
	v_mov_b32_e32 v9, v6
	v_and_b32_e32 v6, 0xffff0000, v3
	v_mul_f32_e32 v3, 0xbfb8aa3b, v6
	v_add_f32_e32 v4, 1.0, v4
	v_rcp_f32_e32 v4, v4
	v_exp_f32_e32 v3, v3
	v_mul_f32_e32 v5, v10, v71
	v_mul_f32_e32 v12, v12, v13
	v_pk_mul_f32 v[4:5], v[4:5], v[8:9]
	v_add_f32_e32 v3, 1.0, v3
	v_mul_f32_e32 v8, v4, v5
	v_rcp_f32_e32 v4, v3
	v_mul_f32_e32 v5, v11, v71
	v_cvt_pk_bf16_f32 v2, v12, v2
	v_pk_mul_f32 v[4:5], v[4:5], v[6:7]
	s_nop 0
	v_mul_f32_e32 v3, v4, v5
	v_cvt_pk_bf16_f32 v3, v8, v3
	global_store_dwordx4 v[74:75], v[0:3], off offset:48
	s_barrier
	s_cbranch_scc0 .LBB0_487
